# k16 + conv2d gelu select (v_cmp + v_cndmask per element) replaced by one v_max_f32 of the two candidates (exact for this pair): 32 fewer VALU per item
# speedup vs baseline: 1.0114x; 1.0026x over previous
; __device__ __forceinline__ void conv2d_phase(const Frame& F, int l, bool with_ctx, bool dry) {
;     ...
;     for (int it = gw; it < total; it += NGW) {
;         const bool isctx = it >= NLAT;
;         const int q = isctx ? it - NLAT : it, cc = q % 11, seg = q / 11;
;         int tok0, c0, wlim; bool up_ok, dn_ok;
;         if (!isctx) { const int b = seg >> 10, r = (seg >> 3) & 127; c0 = (seg & 7) * 8; tok0 = b * SEQ + r * GRIDW + c0; wlim = GRIDW; up_ok = r > 0; dn_ok = r < SEQ / GRIDW - 1; }
;         else { const int b = seg >> 5; c0 = (seg & 31) * 8; tok0 = ML + b * CTXL + c0; wlim = CTXL; up_ok = false; dn_ok = false; }
;         const int ch = cc * 256 + lane * 4;
;         const float* wq = W9 + ch;
;         f32x4 w[9];
; #pragma unroll
;         for (int k = 0; k < 9; ++k) w[k] = *(const f32x4*)(wq + (size_t)k * FFN);
;         const f32x4 bias4 = *(const f32x4*)(Bc + ch);
;         const bf16_t* ubase = UV + (size_t)tok0 * NUP + ch;
;         u32x2 u[3][10];
; #pragma unroll
;         for (int dy = 0; dy < 3; ++dy) {
;             const bool rok = dy == 1 ? true : (dy == 0 ? up_ok : dn_ok);
; #pragma unroll
;             for (int j = 0; j < 10; ++j) {
;                 const int col = c0 - 1 + j; const bool ok = rok && col >= 0 && col < wlim;
;                 const unsigned msk = (unsigned)-(int)ok;
;                 const long off = (long)(((dy - 1) * GRIDW + (j - 1)) & (int)msk) * NUP;
;                 const u32x2 t = *(const u32x2*)(ubase + off);
;                 u[dy][j] = (u32x2){t.x & msk, t.y & msk};
;             }
;         }
.LBB0_2037:
	s_add_i32 s4, s6, -1
	s_or_b32 s5, s6, 1
	s_or_b32 s8, s6, 2
	s_or_b32 s9, s6, 3
	s_or_b32 s10, s6, 4
	s_or_b32 s11, s6, 5
	s_or_b32 s17, s6, 6
	s_or_b32 s28, s6, 7
	s_add_i32 s16, s6, 8
	s_cmp_lt_u32 s4, s7
	s_cselect_b64 s[0:1], -1, 0
	s_and_b64 s[0:1], s[0:1], exec
	s_cselect_b32 s75, -1, 0
	s_cmp_lt_u32 s16, s7
	s_cselect_b64 s[38:39], -1, 0
	s_and_b64 s[0:1], s[38:39], exec
	s_cselect_b32 s16, 0x16000, 0
	s_cmp_lt_u32 s28, s7
	s_cselect_b64 s[40:41], -1, 0
	s_and_b64 s[0:1], s[40:41], exec
	s_cselect_b32 s92, 0x13400, 0
	s_cmp_lt_u32 s17, s7
	s_cselect_b64 s[42:43], -1, 0
	s_and_b64 s[0:1], s[42:43], exec
	s_cselect_b32 s68, 0x10800, 0
	s_cmp_lt_u32 s11, s7
	s_cselect_b64 s[44:45], -1, 0
	s_and_b64 s[0:1], s[44:45], exec
	s_cselect_b32 s66, 0xdc00, 0
	s_cmp_lt_u32 s10, s7
	s_cselect_b64 s[76:77], -1, 0
	s_and_b64 s[0:1], s[76:77], exec
	s_cselect_b32 s10, 0xb000, 0
	s_cmp_lt_u32 s9, s7
	s_cselect_b64 s[82:83], -1, 0
	s_and_b64 s[0:1], s[82:83], exec
	s_cselect_b32 s62, 0x8400, 0
	s_cmp_lt_u32 s8, s7
	s_cselect_b64 s[64:65], -1, 0
	s_and_b64 s[0:1], s[64:65], exec
	s_cselect_b32 s88, 0x5800, 0
	s_cmp_lt_u32 s5, s7
	s_cselect_b64 vcc, -1, 0
	s_and_b64 s[0:1], vcc, exec
	s_cselect_b32 s28, 0x2c00, 0
	s_cmp_lt_u32 s4, s7
	s_cselect_b64 s[0:1], -1, 0
	s_mul_i32 s3, s3, 11
	s_and_b64 s[4:5], s[0:1], exec
	s_cselect_b32 s74, 0xffffd400, 0
	s_sub_i32 s2, s2, s3
	v_lshl_add_u32 v42, s2, 8, v0
	v_ashrrev_i32_e32 v43, 31, v42
	v_readlane_b32 s2, v255, 21
	v_lshlrev_b64 v[38:39], 2, v[42:43]
	v_readlane_b32 s3, v255, 22
	v_readlane_b32 s4, v254, 19
	v_readlane_b32 s5, v254, 20
	s_waitcnt lgkmcnt(0)
	v_lshl_add_u64 v[2:3], s[2:3], 0, v[38:39]
	s_movk_i32 s2, 0x2000
	v_add_co_u32_e64 v4, s[2:3], s2, v2
	s_mov_b32 s11, s29
	s_nop 0
	v_addc_co_u32_e64 v5, s[2:3], 0, v3, s[2:3]
	s_movk_i32 s2, 0x5000
	s_nop 0
	v_add_co_u32_e64 v6, s[2:3], s2, v2
	s_mov_b32 s89, s29
	s_nop 0
	v_addc_co_u32_e64 v7, s[2:3], 0, v3, s[2:3]
	s_mov_b32 s2, 0x8000
	s_nop 0
	v_add_co_u32_e64 v8, s[2:3], s2, v2
	s_mov_b32 s63, s29
	s_nop 0
	v_addc_co_u32_e64 v9, s[2:3], 0, v3, s[2:3]
	s_mov_b32 s2, 0xb000
	s_nop 0
	v_add_co_u32_e64 v10, s[2:3], s2, v2
	s_mov_b32 s67, s29
	s_nop 0
	v_addc_co_u32_e64 v11, s[2:3], 0, v3, s[2:3]
	s_mov_b32 s2, 0xd000
	s_nop 0
	v_add_co_u32_e64 v12, s[2:3], s2, v2
	s_mov_b32 s69, s29
	s_nop 0
	v_addc_co_u32_e64 v13, s[2:3], 0, v3, s[2:3]
	s_mov_b32 s2, 0x10000
	s_nop 0
	v_add_co_u32_e64 v14, s[2:3], s2, v2
	s_mov_b32 s93, s29
	s_nop 0
	v_addc_co_u32_e64 v15, s[2:3], 0, v3, s[2:3]
	s_mov_b32 s2, 0x13000
	s_nop 0
	v_add_co_u32_e64 v40, s[2:3], s2, v2
	s_mov_b32 s17, s29
	s_nop 0
	v_addc_co_u32_e64 v41, s[2:3], 0, v3, s[2:3]
	s_mov_b32 s2, 0x16000
	s_nop 0
	v_add_co_u32_e64 v44, s[2:3], s2, v2
	s_mov_b32 s36, 0x3f07dc22
	s_nop 0
	v_addc_co_u32_e64 v45, s[2:3], 0, v3, s[2:3]
	s_mul_i32 s2, s27, 0x2c00
	s_mul_hi_i32 s3, s27, 0x2c00
	s_add_u32 s2, s4, s2
	s_addc_u32 s3, s5, s3
	s_and_b64 s[4:5], s[70:71], s[0:1]
	v_lshl_add_u64 v[68:69], v[42:43], 1, s[2:3]
	s_and_b64 s[2:3], s[4:5], exec
	s_cselect_b32 s3, -1, 0
	s_cselect_b32 s2, 0xfff4d400, 0
	v_lshl_add_u64 v[16:17], v[68:69], 0, s[2:3]
	global_load_dwordx2 v[16:17], v[16:17], off
	s_cmp_lt_u32 s6, s7
	s_cselect_b64 s[2:3], -1, 0
	s_and_b64 s[6:7], s[70:71], s[2:3]
	s_and_b64 s[8:9], s[6:7], exec
	s_cselect_b32 s9, -1, 0
	s_cselect_b32 s8, 0xfff50000, 0
	v_lshl_add_u64 v[18:19], v[68:69], 0, s[8:9]
	s_and_b64 s[8:9], s[70:71], vcc
	s_and_b64 s[72:73], s[8:9], exec
	s_cselect_b32 s73, -1, 0
	s_cselect_b32 s72, 0xfff52c00, 0
	v_lshl_add_u64 v[20:21], v[68:69], 0, s[72:73]
	s_and_b64 s[46:47], s[70:71], s[64:65]
	s_and_b64 s[72:73], s[46:47], exec
	s_cselect_b32 s73, -1, 0
	s_cselect_b32 s72, 0xfff55800, 0
	v_lshl_add_u64 v[46:47], v[68:69], 0, s[72:73]
	v_lshl_add_u64 v[70:71], v[68:69], 0, s[10:11]
	v_lshl_add_u64 v[62:63], v[68:69], 0, s[88:89]
	v_lshl_add_u64 v[64:65], v[68:69], 0, s[62:63]
	s_mov_b64 s[50:51], s[46:47]
	s_mov_b32 s46, 0xbf38aa3b
	s_mov_b64 s[88:89], s[44:45]
	global_load_dwordx2 v[150:151], v[18:19], off
	global_load_dwordx2 v[152:153], v[20:21], off
	v_lshl_add_u64 v[154:155], v[68:69], 0, s[74:75]
	v_lshl_add_u64 v[162:163], v[68:69], 0, s[28:29]
	global_load_dwordx2 v[156:157], v[154:155], off
	global_load_dwordx2 v[158:159], v[68:69], off
	global_load_dwordx2 v[160:161], v[162:163], off
	s_waitcnt vmcnt(5)
	v_cndmask_b32_e64 v109, 0, v16, s[4:5]
	v_cndmask_b32_e64 v108, 0, v17, s[4:5]
	v_lshlrev_b32_e32 v110, 16, v109
	v_and_b32_e32 v111, 0xffff0000, v109
	s_waitcnt vmcnt(4)
	v_cndmask_b32_e64 v107, 0, v150, s[6:7]
	v_cndmask_b32_e64 v106, 0, v151, s[6:7]
	v_lshlrev_b32_e32 v116, 16, v107
	v_and_b32_e32 v117, 0xffff0000, v107
	v_lshlrev_b32_e32 v118, 16, v106
	v_and_b32_e32 v119, 0xffff0000, v106
	s_waitcnt vmcnt(3)
	v_cndmask_b32_e64 v105, 0, v152, s[8:9]
	v_cndmask_b32_e64 v104, 0, v153, s[8:9]
	s_and_b64 s[8:9], s[70:71], s[82:83]
	s_and_b64 s[4:5], s[8:9], exec
	s_cselect_b32 s5, -1, 0
	s_cselect_b32 s4, 0xfff58400, 0
	s_and_b64 s[6:7], s[70:71], s[76:77]
	v_lshl_add_u64 v[48:49], v[68:69], 0, s[4:5]
	s_and_b64 s[4:5], s[6:7], exec
	s_cselect_b32 s5, -1, 0
	s_cselect_b32 s4, 0xfff5b000, 0
	v_lshl_add_u64 v[50:51], v[68:69], 0, s[4:5]
	s_and_b64 s[4:5], s[70:71], s[44:45]
	v_writelane_b32 v255, s4, 27
	v_lshlrev_b32_e32 v112, 16, v104
	v_and_b32_e32 v113, 0xffff0000, v104
	v_writelane_b32 v255, s5, 28
	s_and_b64 s[4:5], s[4:5], exec
	s_cselect_b32 s5, -1, 0
	s_cselect_b32 s4, 0xfff5dc00, 0
	v_lshl_add_u64 v[52:53], v[68:69], 0, s[4:5]
	s_and_b64 s[4:5], s[70:71], s[42:43]
	v_writelane_b32 v255, s4, 25
	s_mov_b64 s[74:75], s[42:43]
	s_waitcnt vmcnt(2)
; __device__ __forceinline__ void conv2d_phase(const Frame& F, int l, bool with_ctx, bool dry) {
;     ...
;         const int ch = cc * 256 + lane * 4;
;         const float* wq = W9 + ch;
;         f32x4 w[9];
; #pragma unroll
;         for (int k = 0; k < 9; ++k) w[k] = *(const f32x4*)(wq + (size_t)k * FFN);
;         const f32x4 bias4 = *(const f32x4*)(Bc + ch);
;         const bf16_t* ubase = UV + (size_t)tok0 * NUP + ch;
;         u32x2 u[3][10];
; #pragma unroll
;         for (int dy = 0; dy < 3; ++dy) {
;             const bool rok = dy == 1 ? true : (dy == 0 ? up_ok : dn_ok);
; #pragma unroll
;             for (int j = 0; j < 10; ++j) {
;                 const int col = c0 - 1 + j; const bool ok = rok && col >= 0 && col < wlim;
;                 const unsigned msk = (unsigned)-(int)ok;
;                 const long off = (long)(((dy - 1) * GRIDW + (j - 1)) & (int)msk) * NUP;
;                 const u32x2 t = *(const u32x2*)(ubase + off);
;                 u[dy][j] = (u32x2){t.x & msk, t.y & msk};
;             }
;         }
;         u32x2 vv[8];
; #pragma unroll
;         for (int t = 0; t < 8; ++t) vv[t] = *(const u32x2*)(ubase + (size_t)t * NUP + FFN);
	v_cndmask_b32_e64 v123, 0, v156, s[0:1]
	v_writelane_b32 v255, s5, 26
	s_and_b64 s[4:5], s[4:5], exec
	s_cselect_b32 s5, -1, 0
	s_cselect_b32 s4, 0xfff60800, 0
	v_lshl_add_u64 v[54:55], v[68:69], 0, s[4:5]
	s_and_b64 s[4:5], s[70:71], s[40:41]
	v_writelane_b32 v255, s4, 23
	v_cndmask_b32_e64 v120, 0, v157, s[0:1]
	s_waitcnt vmcnt(1)
	v_cndmask_b32_e64 v121, 0, v158, s[2:3]
	v_writelane_b32 v255, s5, 24
	s_and_b64 s[4:5], s[4:5], exec
	s_cselect_b32 s5, -1, 0
	s_cselect_b32 s4, 0xfff63400, 0
	s_and_b64 s[72:73], s[70:71], s[38:39]
	v_lshl_add_u64 v[56:57], v[68:69], 0, s[4:5]
	s_and_b64 s[4:5], s[72:73], exec
	s_cselect_b32 s5, -1, 0
	s_cselect_b32 s4, 0xfff66000, 0
	s_and_b64 s[0:1], s[30:31], s[0:1]
	v_lshl_add_u64 v[58:59], v[68:69], 0, s[4:5]
	s_and_b64 s[4:5], s[0:1], exec
	v_cndmask_b32_e64 v122, 0, v159, s[2:3]
	s_cselect_b32 s28, 0xad400, 0
	s_and_b64 s[2:3], s[30:31], s[2:3]
	s_and_b64 s[4:5], s[2:3], exec
	v_lshl_add_u64 v[16:17], v[68:69], 0, s[28:29]
	s_cselect_b32 s28, 0xb0000, 0
	global_load_dwordx2 v[72:73], v[16:17], off
	v_lshl_add_u64 v[16:17], v[68:69], 0, s[28:29]
	global_load_dwordx2 v[74:75], v[16:17], off
	s_waitcnt vmcnt(2)
	v_cndmask_b32_e32 v115, 0, v160, vcc
	v_cndmask_b32_e32 v114, 0, v161, vcc
	s_and_b64 vcc, s[30:31], vcc
	s_and_b64 s[4:5], vcc, exec
	s_cselect_b32 s28, 0xb2c00, 0
	v_lshl_add_u64 v[16:17], v[68:69], 0, s[28:29]
	global_load_dwordx2 v[76:77], v[16:17], off
	global_load_dwordx4 v[34:37], v[2:3], off
	global_load_dwordx4 v[18:21], v[4:5], off offset:3072
	global_load_dwordx4 v[22:25], v[6:7], off offset:2048
	global_load_dwordx4 v[26:29], v[8:9], off offset:1024
	global_load_dwordx4 v[30:33], v[10:11], off
	s_nop 0
	global_load_dwordx4 v[10:13], v[12:13], off offset:3072
	s_nop 0
	global_load_dwordx4 v[14:17], v[14:15], off offset:2048
	s_nop 0
	global_load_dwordx4 v[2:5], v[40:41], off offset:1024
	global_load_dwordx4 v[6:9], v[44:45], off
	v_readlane_b32 s4, v255, 55
	v_readlane_b32 s5, v255, 56
	v_lshlrev_b32_e32 v138, 16, v123
	v_and_b32_e32 v139, 0xffff0000, v123
	v_lshl_add_u64 v[38:39], s[4:5], 0, v[38:39]
	s_and_b64 s[4:5], s[30:31], s[64:65]
	global_load_dwordx4 v[38:41], v[38:39], off
	s_nop 0
	global_load_dwordx2 v[92:93], v[46:47], off
	global_load_dwordx2 v[80:81], v[48:49], off
	global_load_dwordx2 v[66:67], v[50:51], off
	global_load_dwordx2 v[60:61], v[52:53], off
	s_nop 0
	global_load_dwordx2 v[54:55], v[54:55], off
	s_nop 0
	global_load_dwordx2 v[48:49], v[56:57], off
	global_load_dwordx2 v[44:45], v[58:59], off
	global_load_dwordx2 v[94:95], v[62:63], off
	global_load_dwordx2 v[82:83], v[64:65], off
	s_nop 0
	global_load_dwordx2 v[70:71], v[70:71], off
	v_lshl_add_u64 v[46:47], v[68:69], 0, s[66:67]
	global_load_dwordx2 v[64:65], v[46:47], off
	v_lshlrev_b32_e32 v140, 16, v120
	v_and_b32_e32 v141, 0xffff0000, v120
	v_lshlrev_b32_e32 v120, 16, v121
	v_and_b32_e32 v121, 0xffff0000, v121
	v_lshlrev_b32_e32 v104, 16, v115
	v_lshlrev_b32_e32 v124, 16, v122
	v_and_b32_e32 v125, 0xffff0000, v122
	v_lshlrev_b32_e32 v106, 16, v114
	v_and_b32_e32 v107, 0xffff0000, v114
	s_mov_b64 s[66:67], s[38:39]
	s_mov_b64 s[70:71], s[40:41]
	s_waitcnt vmcnt(23)
	v_cndmask_b32_e64 v133, 0, v72, s[0:1]
	v_cndmask_b32_e64 v132, 0, v73, s[0:1]
	s_and_b64 s[0:1], s[4:5], exec
	s_waitcnt vmcnt(22)
	v_cndmask_b32_e64 v126, 0, v74, s[2:3]
	v_cndmask_b32_e64 v127, 0, v75, s[2:3]
	s_cselect_b32 s28, 0xb5800, 0
	s_and_b64 s[2:3], s[30:31], s[82:83]
	s_and_b64 s[0:1], s[2:3], exec
	v_lshl_add_u64 v[50:51], v[68:69], 0, s[28:29]
	s_cselect_b32 s28, 0xb8400, 0
	s_and_b64 s[0:1], s[30:31], s[76:77]
	s_and_b64 s[10:11], s[0:1], exec
	global_load_dwordx2 v[100:101], v[50:51], off
	v_lshl_add_u64 v[50:51], v[68:69], 0, s[28:29]
	s_cselect_b32 s28, 0xbb000, 0
	s_and_b64 s[62:63], s[30:31], s[44:45]
	v_lshl_add_u64 v[46:47], v[68:69], 0, s[68:69]
	s_and_b64 s[10:11], s[62:63], exec
	global_load_dwordx2 v[58:59], v[46:47], off
	global_load_dwordx2 v[90:91], v[50:51], off
	v_lshl_add_u64 v[50:51], v[68:69], 0, s[28:29]
	s_cselect_b32 s28, 0xbdc00, 0
	s_and_b64 s[68:69], s[30:31], s[42:43]
	v_lshl_add_u64 v[46:47], v[68:69], 0, s[92:93]
	s_and_b64 s[10:11], s[68:69], exec
	global_load_dwordx2 v[52:53], v[46:47], off
	global_load_dwordx2 v[84:85], v[50:51], off
	v_lshl_add_u64 v[46:47], v[68:69], 0, s[16:17]
	v_lshl_add_u64 v[50:51], v[68:69], 0, s[28:29]
	s_cselect_b32 s28, 0xc0800, 0
	s_and_b64 s[16:17], s[30:31], s[40:41]
	s_and_b64 s[10:11], s[16:17], exec
	global_load_dwordx2 v[46:47], v[46:47], off
	s_waitcnt vmcnt(27)
	v_cndmask_b32_e32 v131, 0, v76, vcc
	global_load_dwordx2 v[72:73], v[50:51], off
	v_lshl_add_u64 v[50:51], v[68:69], 0, s[28:29]
	s_cselect_b32 s28, 0xc3400, 0
	s_and_b64 s[10:11], s[30:31], s[38:39]
	s_and_b64 s[30:31], s[10:11], exec
	global_load_dwordx2 v[62:63], v[50:51], off
	v_lshl_add_u64 v[50:51], v[68:69], 0, s[28:29]
	s_cselect_b32 s28, 0xc6000, 0
	global_load_dwordx2 v[56:57], v[50:51], off
	v_lshl_add_u64 v[50:51], v[68:69], 0, s[28:29]
	s_movk_i32 s28, 0x1000
	v_cndmask_b32_e32 v130, 0, v77, vcc
	v_add_co_u32_e32 v74, vcc, s28, v68
	s_movk_i32 s28, 0x4000
	s_nop 0
	v_addc_co_u32_e32 v75, vcc, 0, v69, vcc
	global_load_dwordx2 v[102:103], v[74:75], off offset:1536
	v_add_co_u32_e32 v74, vcc, s28, v68
	s_movk_i32 s28, 0x6000
	s_nop 0
	v_addc_co_u32_e32 v75, vcc, 0, v69, vcc
	global_load_dwordx2 v[50:51], v[50:51], off
	s_waitcnt vmcnt(22)
; __device__ __forceinline__ unsigned pk2(float lo, float hi) { const f32x2 v = {lo, hi}; const bf16x2_t b = __builtin_convertvector(v, bf16x2_t); return __builtin_bit_cast(unsigned, b); }
; __device__ __forceinline__ f32x2 gelu_pk(f32x2 v) {
;     const f32x2 av = __builtin_elementwise_abs(v), d = av * 0.2316418882f + 1.0f;
;     f32x2 t; t.x = __builtin_amdgcn_rcpf(d.x); t.y = __builtin_amdgcn_rcpf(d.y);
;     f32x2 q = t * 0.5307027145f + (-0.7265760135f); q = q * t + 0.7107068705f; q = q * t + (-0.142248368f); q = q * t + 0.127414796f; q = q * t;
;     const f32x2 s = (v * v) * (-0.72134752044f);
;     f32x2 e; e.x = __builtin_amdgcn_exp2f(s.x); e.y = __builtin_amdgcn_exp2f(s.y);
;     const f32x2 m = v * (q * e), r = v - m;
;     f32x2 o; o.x = v.x < 0.f ? m.x : r.x; o.y = v.y < 0.f ? m.y : r.y; return o;
; __device__ __forceinline__ void conv2d_phase(const Frame& F, int l, bool with_ctx, bool dry) {
;     ...
;         for (int t = 0; t < 8; ++t) {
;             f32x4 a = bias4;
; #pragma unroll
;             for (int dy = 0; dy < 3; ++dy)
; #pragma unroll
;                 for (int dx = 0; dx < 3; ++dx) {
;                     const u32x2 x = u[dy][t + dx]; const f32x4 ww = w[dy * 3 + dx];
;                     a.x += ww.x * bflo(x.x); a.y += ww.y * bfhi(x.x); a.z += ww.z * bflo(x.y); a.w += ww.w * bfhi(x.y);
;                 }
;             const f32x2 g0 = gelu_pk((f32x2){a.x, a.y}), g1 = gelu_pk((f32x2){a.z, a.w});
;             u32x2 o; o.x = pk2(g0.x * bflo(vv[t].x), g0.y * bfhi(vv[t].x)); o.y = pk2(g1.x * bflo(vv[t].y), g1.y * bfhi(vv[t].y));
;             bf16_t* vp = UV + (size_t)(tok0 + t) * NUP + FFN + ch;
;             if (!dry) *(u32x2*)vp = o; else asm volatile("" :: "v"(o));
	v_pk_fma_f32 v[134:135], v[34:35], v[110:111], v[38:39]
	global_load_dwordx2 v[96:97], v[74:75], off offset:512
	v_add_co_u32_e32 v74, vcc, s28, v68
	s_mov_b32 s28, 0x9000
	s_nop 0
	v_addc_co_u32_e32 v75, vcc, 0, v69, vcc
	global_load_dwordx2 v[98:99], v[74:75], off offset:3584
	v_add_co_u32_e32 v74, vcc, s28, v68
	s_mov_b32 s28, 0xc000
	s_nop 0
	v_addc_co_u32_e32 v75, vcc, 0, v69, vcc
	global_load_dwordx2 v[86:87], v[74:75], off offset:2560
	v_add_co_u32_e32 v74, vcc, s28, v68
	s_mov_b32 s28, 0xf000
	s_nop 0
	v_addc_co_u32_e32 v75, vcc, 0, v69, vcc
	global_load_dwordx2 v[76:77], v[74:75], off offset:1536
	v_add_co_u32_e32 v74, vcc, s28, v68
	s_mov_b32 s28, 0x11000
	s_nop 0
	v_addc_co_u32_e32 v75, vcc, 0, v69, vcc
	global_load_dwordx2 v[88:89], v[74:75], off offset:512
	v_add_co_u32_e32 v74, vcc, s28, v68
	s_mov_b32 s28, 0x14000
	s_nop 0
	v_addc_co_u32_e32 v75, vcc, 0, v69, vcc
	global_load_dwordx2 v[78:79], v[74:75], off offset:3584
	v_add_co_u32_e32 v74, vcc, s28, v68
	v_lshlrev_b32_e32 v110, 16, v108
	s_nop 0
	v_addc_co_u32_e32 v75, vcc, 0, v69, vcc
	global_load_dwordx2 v[74:75], v[74:75], off offset:2560
	v_and_b32_e32 v111, 0xffff0000, v108
	v_pk_fma_f32 v[136:137], v[36:37], v[110:111], v[40:41]
	v_lshlrev_b32_e32 v110, 16, v105
	v_and_b32_e32 v111, 0xffff0000, v105
	v_lshlrev_b32_e32 v142, 16, v133
	v_and_b32_e32 v143, 0xffff0000, v133
	v_lshlrev_b32_e32 v144, 16, v132
	v_and_b32_e32 v145, 0xffff0000, v132
	v_pk_fma_f32 v[132:133], v[18:19], v[116:117], v[134:135]
	v_and_b32_e32 v105, 0xffff0000, v115
	v_pk_fma_f32 v[132:133], v[22:23], v[110:111], v[132:133]
	v_lshlrev_b32_e32 v122, 16, v126
	v_pk_fma_f32 v[132:133], v[26:27], v[138:139], v[132:133]
	v_and_b32_e32 v123, 0xffff0000, v126
	v_pk_fma_f32 v[132:133], v[30:31], v[120:121], v[132:133]
	v_lshlrev_b32_e32 v108, 16, v131
	v_pk_fma_f32 v[132:133], v[10:11], v[104:105], v[132:133]
	v_and_b32_e32 v109, 0xffff0000, v131
	v_pk_fma_f32 v[132:133], v[14:15], v[142:143], v[132:133]
	s_mov_b32 s28, 0x3e6d3388
	v_pk_fma_f32 v[132:133], v[2:3], v[122:123], v[132:133]
	v_lshlrev_b32_e32 v114, 16, v130
	v_pk_fma_f32 v[132:133], v[6:7], v[108:109], v[132:133]
	v_and_b32_e32 v115, 0xffff0000, v130
	v_and_b32_e32 v135, 0x7fffffff, v133
	v_and_b32_e32 v134, 0x7fffffff, v132
	v_pk_fma_f32 v[134:135], v[134:135], s[28:29], 1.0 op_sel_hi:[1,0,0]
	v_pk_fma_f32 v[130:131], v[20:21], v[118:119], v[136:137]
	v_rcp_f32_e32 v134, v134
	v_rcp_f32_e32 v135, v135
	v_pk_fma_f32 v[130:131], v[24:25], v[112:113], v[130:131]
	s_mov_b32 s38, 0xbf3a00e3
	v_pk_fma_f32 v[130:131], v[28:29], v[140:141], v[130:131]
	v_mov_b64_e32 v[136:137], s[38:39]
	v_pk_mul_f32 v[140:141], v[132:133], v[132:133]
	v_pk_fma_f32 v[130:131], v[32:33], v[124:125], v[130:131]
	v_pk_fma_f32 v[138:139], v[134:135], s[36:37], v[136:137] op_sel_hi:[1,0,0]
	s_mov_b32 s40, 0x3f35f0e3
	v_pk_mul_f32 v[140:141], v[140:141], s[46:47] op_sel_hi:[1,0]
	v_pk_fma_f32 v[130:131], v[12:13], v[106:107], v[130:131]
	v_pk_fma_f32 v[138:139], v[134:135], v[138:139], s[40:41] op_sel_hi:[1,1,0]
	s_mov_b32 s42, 0xbe11a98e
	v_exp_f32_e32 v140, v140
	v_exp_f32_e32 v141, v141
	v_lshlrev_b32_e32 v126, 16, v127
	v_and_b32_e32 v127, 0xffff0000, v127
	v_pk_fma_f32 v[130:131], v[16:17], v[144:145], v[130:131]
	v_pk_fma_f32 v[138:139], v[134:135], v[138:139], s[42:43] op_sel_hi:[1,1,0]
	s_mov_b32 s44, 0x3e027906
	v_pk_fma_f32 v[130:131], v[4:5], v[126:127], v[130:131]
	v_pk_fma_f32 v[138:139], v[134:135], v[138:139], s[44:45] op_sel_hi:[1,1,0]
	v_pk_fma_f32 v[130:131], v[8:9], v[114:115], v[130:131]
	v_pk_mul_f32 v[134:135], v[134:135], v[138:139]
	v_pk_mul_f32 v[134:135], v[140:141], v[134:135]
	v_and_b32_e32 v141, 0x7fffffff, v131
	v_and_b32_e32 v140, 0x7fffffff, v130
	v_pk_fma_f32 v[140:141], v[140:141], s[28:29], 1.0 op_sel_hi:[1,0,0]
	v_pk_mul_f32 v[138:139], v[132:133], v[134:135]
	v_rcp_f32_e32 v140, v140
	v_rcp_f32_e32 v141, v141
	v_pk_fma_f32 v[134:135], v[132:133], v[134:135], v[132:133] neg_lo:[1,0,0] neg_hi:[1,0,0]
	s_mov_b64 s[30:31], -1
	v_max_f32_e32 v133, v135, v139
	s_waitcnt vmcnt(8)
	v_and_b32_e32 v139, 0xffff0000, v102
	v_max_f32_e32 v132, v134, v138
	v_pk_fma_f32 v[134:135], v[140:141], s[36:37], v[136:137] op_sel_hi:[1,0,0]
	v_pk_mul_f32 v[136:137], v[130:131], v[130:131]
	v_pk_fma_f32 v[134:135], v[140:141], v[134:135], s[40:41] op_sel_hi:[1,1,0]
	v_pk_mul_f32 v[136:137], v[136:137], s[46:47] op_sel_hi:[1,0]
	v_pk_fma_f32 v[134:135], v[140:141], v[134:135], s[42:43] op_sel_hi:[1,1,0]
	v_exp_f32_e32 v136, v136
	v_exp_f32_e32 v137, v137
	v_pk_fma_f32 v[134:135], v[140:141], v[134:135], s[44:45] op_sel_hi:[1,1,0]
	v_pk_mul_f32 v[134:135], v[140:141], v[134:135]
	v_lshlrev_b32_e32 v138, 16, v102
	v_pk_mul_f32 v[134:135], v[136:137], v[134:135]
	v_pk_mul_f32 v[132:133], v[132:133], v[138:139]
	v_pk_mul_f32 v[136:137], v[130:131], v[134:135]
	v_pk_fma_f32 v[134:135], v[130:131], v[134:135], v[130:131] neg_lo:[1,0,0] neg_hi:[1,0,0]
	v_cvt_pk_bf16_f32 v102, v132, v133
	v_max_f32_e32 v131, v135, v137
	v_lshlrev_b32_e32 v132, 16, v103
	v_and_b32_e32 v133, 0xffff0000, v103
	v_max_f32_e32 v130, v134, v136
	v_pk_mul_f32 v[130:131], v[130:131], v[132:133]
	s_and_b64 vcc, exec, s[48:49]
	v_cvt_pk_bf16_f32 v103, v130, v131
	s_cbranch_vccz .LBB0_2039
	s_mov_b64 s[30:31], 0

; __device__ __forceinline__ unsigned pk2(float lo, float hi) { const f32x2 v = {lo, hi}; const bf16x2_t b = __builtin_convertvector(v, bf16x2_t); return __builtin_bit_cast(unsigned, b); }
; __device__ __forceinline__ f32x2 gelu_pk(f32x2 v) {
;     const f32x2 av = __builtin_elementwise_abs(v), d = av * 0.2316418882f + 1.0f;
;     f32x2 t; t.x = __builtin_amdgcn_rcpf(d.x); t.y = __builtin_amdgcn_rcpf(d.y);
;     f32x2 q = t * 0.5307027145f + (-0.7265760135f); q = q * t + 0.7107068705f; q = q * t + (-0.142248368f); q = q * t + 0.127414796f; q = q * t;
;     const f32x2 s = (v * v) * (-0.72134752044f);
;     f32x2 e; e.x = __builtin_amdgcn_exp2f(s.x); e.y = __builtin_amdgcn_exp2f(s.y);
;     const f32x2 m = v * (q * e), r = v - m;
;     f32x2 o; o.x = v.x < 0.f ? m.x : r.x; o.y = v.y < 0.f ? m.y : r.y; return o;
; __device__ __forceinline__ void conv2d_phase(const Frame& F, int l, bool with_ctx, bool dry) {
;     ...
;         for (int t = 0; t < 8; ++t) {
;             f32x4 a = bias4;
; #pragma unroll
;             for (int dy = 0; dy < 3; ++dy)
; #pragma unroll
;                 for (int dx = 0; dx < 3; ++dx) {
;                     const u32x2 x = u[dy][t + dx]; const f32x4 ww = w[dy * 3 + dx];
;                     a.x += ww.x * bflo(x.x); a.y += ww.y * bfhi(x.x); a.z += ww.z * bflo(x.y); a.w += ww.w * bfhi(x.y);
;                 }
;             const f32x2 g0 = gelu_pk((f32x2){a.x, a.y}), g1 = gelu_pk((f32x2){a.z, a.w});
;             u32x2 o; o.x = pk2(g0.x * bflo(vv[t].x), g0.y * bfhi(vv[t].x)); o.y = pk2(g1.x * bflo(vv[t].y), g1.y * bfhi(vv[t].y));
;             bf16_t* vp = UV + (size_t)(tok0 + t) * NUP + FFN + ch;
;             if (!dry) *(u32x2*)vp = o; else asm volatile("" :: "v"(o));
.LBB0_2041:
	v_cndmask_b32_e64 v68, 0, v92, s[50:51]
	v_pk_fma_f32 v[102:103], v[34:35], v[116:117], v[38:39]
	v_lshlrev_b32_e32 v116, 16, v68
	v_and_b32_e32 v117, 0xffff0000, v68
	v_pk_fma_f32 v[102:103], v[18:19], v[110:111], v[102:103]
	v_cndmask_b32_e64 v69, 0, v93, s[50:51]
	v_pk_fma_f32 v[102:103], v[22:23], v[116:117], v[102:103]
	v_cndmask_b32_e64 v92, 0, v94, s[64:65]
	v_pk_fma_f32 v[102:103], v[26:27], v[120:121], v[102:103]
	v_pk_fma_f32 v[130:131], v[36:37], v[118:119], v[40:41]
	v_lshlrev_b32_e32 v118, 16, v69
	v_and_b32_e32 v119, 0xffff0000, v69
	v_lshlrev_b32_e32 v68, 16, v92
	v_and_b32_e32 v69, 0xffff0000, v92
	v_pk_fma_f32 v[102:103], v[30:31], v[104:105], v[102:103]
	v_cndmask_b32_e64 v93, 0, v95, s[64:65]
	v_pk_fma_f32 v[102:103], v[10:11], v[68:69], v[102:103]
	v_cndmask_b32_e64 v100, 0, v100, s[4:5]
	v_pk_fma_f32 v[102:103], v[14:15], v[122:123], v[102:103]
	v_lshlrev_b32_e32 v94, 16, v93
	v_and_b32_e32 v95, 0xffff0000, v93
	v_lshlrev_b32_e32 v92, 16, v100
	v_and_b32_e32 v93, 0xffff0000, v100
	v_pk_fma_f32 v[102:103], v[2:3], v[108:109], v[102:103]
	v_pk_fma_f32 v[130:131], v[20:21], v[112:113], v[130:131]
	v_pk_fma_f32 v[102:103], v[6:7], v[92:93], v[102:103]
	v_pk_fma_f32 v[130:131], v[24:25], v[118:119], v[130:131]
	v_and_b32_e32 v121, 0x7fffffff, v103
	v_and_b32_e32 v120, 0x7fffffff, v102
	v_pk_fma_f32 v[124:125], v[28:29], v[124:125], v[130:131]
	v_pk_fma_f32 v[120:121], v[120:121], s[28:29], 1.0 op_sel_hi:[1,0,0]
	v_pk_fma_f32 v[124:125], v[32:33], v[106:107], v[124:125]
	v_rcp_f32_e32 v120, v120
	v_rcp_f32_e32 v121, v121
	v_pk_fma_f32 v[124:125], v[12:13], v[94:95], v[124:125]
	v_cndmask_b32_e64 v101, 0, v101, s[4:5]
	v_pk_fma_f32 v[124:125], v[16:17], v[126:127], v[124:125]
	v_pk_mul_f32 v[130:131], v[102:103], v[102:103]
	v_pk_fma_f32 v[122:123], v[4:5], v[114:115], v[124:125]
	v_mov_b64_e32 v[124:125], s[38:39]
	v_lshlrev_b32_e32 v100, 16, v101
	v_and_b32_e32 v101, 0xffff0000, v101
	v_pk_fma_f32 v[126:127], v[120:121], s[36:37], v[124:125] op_sel_hi:[1,0,0]
	v_pk_mul_f32 v[130:131], v[130:131], s[46:47] op_sel_hi:[1,0]
	v_pk_fma_f32 v[122:123], v[8:9], v[100:101], v[122:123]
	v_pk_fma_f32 v[126:127], v[120:121], v[126:127], s[40:41] op_sel_hi:[1,1,0]
	v_exp_f32_e32 v130, v130
	v_exp_f32_e32 v131, v131
	v_pk_fma_f32 v[126:127], v[120:121], v[126:127], s[42:43] op_sel_hi:[1,1,0]
	v_and_b32_e32 v133, 0x7fffffff, v123
	v_and_b32_e32 v132, 0x7fffffff, v122
	v_pk_fma_f32 v[126:127], v[120:121], v[126:127], s[44:45] op_sel_hi:[1,1,0]
	v_pk_fma_f32 v[132:133], v[132:133], s[28:29], 1.0 op_sel_hi:[1,0,0]
	v_pk_mul_f32 v[120:121], v[120:121], v[126:127]
	v_rcp_f32_e32 v132, v132
	v_rcp_f32_e32 v133, v133
	v_pk_mul_f32 v[120:121], v[130:131], v[120:121]
	v_pk_mul_f32 v[130:131], v[102:103], v[120:121]
	v_pk_fma_f32 v[120:121], v[102:103], v[120:121], v[102:103] neg_lo:[1,0,0] neg_hi:[1,0,0]
	s_waitcnt vmcnt(6)
	v_lshlrev_b32_e32 v126, 16, v96
	v_max_f32_e32 v103, v121, v131
	v_and_b32_e32 v127, 0xffff0000, v96
	s_mov_b64 s[4:5], -1
	v_max_f32_e32 v102, v120, v130
	v_pk_fma_f32 v[120:121], v[132:133], s[36:37], v[124:125] op_sel_hi:[1,0,0]
	v_pk_mul_f32 v[124:125], v[122:123], v[122:123]
	v_pk_fma_f32 v[120:121], v[132:133], v[120:121], s[40:41] op_sel_hi:[1,1,0]
	v_pk_mul_f32 v[124:125], v[124:125], s[46:47] op_sel_hi:[1,0]
	v_pk_fma_f32 v[120:121], v[132:133], v[120:121], s[42:43] op_sel_hi:[1,1,0]
	v_exp_f32_e32 v124, v124
	v_exp_f32_e32 v125, v125
	v_pk_fma_f32 v[120:121], v[132:133], v[120:121], s[44:45] op_sel_hi:[1,1,0]
	v_pk_mul_f32 v[120:121], v[132:133], v[120:121]
	v_pk_mul_f32 v[102:103], v[102:103], v[126:127]
	v_pk_mul_f32 v[120:121], v[124:125], v[120:121]
	v_cvt_pk_bf16_f32 v96, v102, v103
	v_pk_mul_f32 v[124:125], v[122:123], v[120:121]
	v_pk_fma_f32 v[120:121], v[122:123], v[120:121], v[122:123] neg_lo:[1,0,0] neg_hi:[1,0,0]
	v_lshlrev_b32_e32 v102, 16, v97
	v_max_f32_e32 v121, v121, v125
	v_and_b32_e32 v103, 0xffff0000, v97
	s_mov_b32 s92, 0x2c000
	v_max_f32_e32 v120, v120, v124
	v_pk_mul_f32 v[102:103], v[120:121], v[102:103]
	s_and_b64 vcc, exec, s[48:49]
	v_cvt_pk_bf16_f32 v97, v102, v103
	s_mov_b32 s93, 0x2e000
	s_cbranch_vccz .LBB0_2043
	s_mov_b64 s[4:5], 0

; __device__ __forceinline__ unsigned pk2(float lo, float hi) { const f32x2 v = {lo, hi}; const bf16x2_t b = __builtin_convertvector(v, bf16x2_t); return __builtin_bit_cast(unsigned, b); }
; __device__ __forceinline__ f32x2 gelu_pk(f32x2 v) {
;     const f32x2 av = __builtin_elementwise_abs(v), d = av * 0.2316418882f + 1.0f;
;     f32x2 t; t.x = __builtin_amdgcn_rcpf(d.x); t.y = __builtin_amdgcn_rcpf(d.y);
;     f32x2 q = t * 0.5307027145f + (-0.7265760135f); q = q * t + 0.7107068705f; q = q * t + (-0.142248368f); q = q * t + 0.127414796f; q = q * t;
;     const f32x2 s = (v * v) * (-0.72134752044f);
;     f32x2 e; e.x = __builtin_amdgcn_exp2f(s.x); e.y = __builtin_amdgcn_exp2f(s.y);
;     const f32x2 m = v * (q * e), r = v - m;
;     f32x2 o; o.x = v.x < 0.f ? m.x : r.x; o.y = v.y < 0.f ? m.y : r.y; return o;
; __device__ __forceinline__ void conv2d_phase(const Frame& F, int l, bool with_ctx, bool dry) {
;     ...
;         for (int t = 0; t < 8; ++t) {
;             f32x4 a = bias4;
; #pragma unroll
;             for (int dy = 0; dy < 3; ++dy)
; #pragma unroll
;                 for (int dx = 0; dx < 3; ++dx) {
;                     const u32x2 x = u[dy][t + dx]; const f32x4 ww = w[dy * 3 + dx];
;                     a.x += ww.x * bflo(x.x); a.y += ww.y * bfhi(x.x); a.z += ww.z * bflo(x.y); a.w += ww.w * bfhi(x.y);
;                 }
;             const f32x2 g0 = gelu_pk((f32x2){a.x, a.y}), g1 = gelu_pk((f32x2){a.z, a.w});
;             u32x2 o; o.x = pk2(g0.x * bflo(vv[t].x), g0.y * bfhi(vv[t].x)); o.y = pk2(g1.x * bflo(vv[t].y), g1.y * bfhi(vv[t].y));
;             bf16_t* vp = UV + (size_t)(tok0 + t) * NUP + FFN + ch;
;             if (!dry) *(u32x2*)vp = o; else asm volatile("" :: "v"(o));
.LBB0_2045:
	v_cndmask_b32_e64 v80, 0, v80, s[8:9]
	v_pk_fma_f32 v[96:97], v[34:35], v[110:111], v[38:39]
	v_lshlrev_b32_e32 v110, 16, v80
	v_and_b32_e32 v111, 0xffff0000, v80
	v_pk_fma_f32 v[96:97], v[18:19], v[116:117], v[96:97]
	v_cndmask_b32_e64 v81, 0, v81, s[8:9]
	v_pk_fma_f32 v[96:97], v[22:23], v[110:111], v[96:97]
	v_cndmask_b32_e64 v82, 0, v82, s[82:83]
	v_pk_fma_f32 v[96:97], v[26:27], v[104:105], v[96:97]
	v_pk_fma_f32 v[120:121], v[36:37], v[112:113], v[40:41]
	v_lshlrev_b32_e32 v112, 16, v81
	v_and_b32_e32 v113, 0xffff0000, v81
	v_lshlrev_b32_e32 v80, 16, v82
	v_and_b32_e32 v81, 0xffff0000, v82
	v_pk_fma_f32 v[96:97], v[30:31], v[68:69], v[96:97]
	v_cndmask_b32_e64 v83, 0, v83, s[82:83]
	v_pk_fma_f32 v[96:97], v[10:11], v[80:81], v[96:97]
	v_cndmask_b32_e64 v102, 0, v90, s[2:3]
	v_pk_fma_f32 v[96:97], v[14:15], v[108:109], v[96:97]
	v_cndmask_b32_e64 v103, 0, v91, s[2:3]
	v_lshlrev_b32_e32 v90, 16, v83
	v_and_b32_e32 v91, 0xffff0000, v83
	v_lshlrev_b32_e32 v82, 16, v102
	v_and_b32_e32 v83, 0xffff0000, v102
	v_pk_fma_f32 v[96:97], v[2:3], v[92:93], v[96:97]
	v_pk_fma_f32 v[120:121], v[20:21], v[118:119], v[120:121]
	v_pk_fma_f32 v[96:97], v[6:7], v[82:83], v[96:97]
	v_pk_fma_f32 v[120:121], v[24:25], v[112:113], v[120:121]
	v_and_b32_e32 v105, 0x7fffffff, v97
	v_and_b32_e32 v104, 0x7fffffff, v96
	v_pk_fma_f32 v[104:105], v[104:105], s[28:29], 1.0 op_sel_hi:[1,0,0]
	v_pk_fma_f32 v[106:107], v[28:29], v[106:107], v[120:121]
	v_rcp_f32_e32 v104, v104
	v_rcp_f32_e32 v105, v105
	v_pk_fma_f32 v[106:107], v[32:33], v[94:95], v[106:107]
	v_mov_b64_e32 v[108:109], s[38:39]
	v_pk_fma_f32 v[106:107], v[12:13], v[90:91], v[106:107]
	v_pk_mul_f32 v[120:121], v[96:97], v[96:97]
	v_pk_fma_f32 v[106:107], v[16:17], v[114:115], v[106:107]
	v_lshlrev_b32_e32 v102, 16, v103
	v_and_b32_e32 v103, 0xffff0000, v103
	v_pk_fma_f32 v[106:107], v[4:5], v[100:101], v[106:107]
	v_pk_fma_f32 v[114:115], v[104:105], s[36:37], v[108:109] op_sel_hi:[1,0,0]
	v_pk_mul_f32 v[120:121], v[120:121], s[46:47] op_sel_hi:[1,0]
	v_pk_fma_f32 v[106:107], v[8:9], v[102:103], v[106:107]
	v_pk_fma_f32 v[114:115], v[104:105], v[114:115], s[40:41] op_sel_hi:[1,1,0]
	v_exp_f32_e32 v120, v120
	v_exp_f32_e32 v121, v121
	v_pk_fma_f32 v[114:115], v[104:105], v[114:115], s[42:43] op_sel_hi:[1,1,0]
	v_and_b32_e32 v123, 0x7fffffff, v107
	v_and_b32_e32 v122, 0x7fffffff, v106
	v_pk_fma_f32 v[114:115], v[104:105], v[114:115], s[44:45] op_sel_hi:[1,1,0]
	v_pk_fma_f32 v[122:123], v[122:123], s[28:29], 1.0 op_sel_hi:[1,0,0]
	v_pk_mul_f32 v[104:105], v[104:105], v[114:115]
	v_rcp_f32_e32 v122, v122
	v_rcp_f32_e32 v123, v123
	v_pk_mul_f32 v[104:105], v[120:121], v[104:105]
	v_pk_mul_f32 v[120:121], v[96:97], v[104:105]
	v_pk_fma_f32 v[104:105], v[96:97], v[104:105], v[96:97] neg_lo:[1,0,0] neg_hi:[1,0,0]
	s_waitcnt vmcnt(5)
	v_lshlrev_b32_e32 v114, 16, v98
	v_max_f32_e32 v97, v105, v121
	v_and_b32_e32 v115, 0xffff0000, v98
	v_lshlrev_b32_e32 v98, 16, v99
	v_max_f32_e32 v96, v104, v120
	v_pk_fma_f32 v[104:105], v[122:123], s[36:37], v[108:109] op_sel_hi:[1,0,0]
	v_pk_mul_f32 v[108:109], v[106:107], v[106:107]
	v_pk_fma_f32 v[104:105], v[122:123], v[104:105], s[40:41] op_sel_hi:[1,1,0]
	v_pk_mul_f32 v[108:109], v[108:109], s[46:47] op_sel_hi:[1,0]
	v_pk_fma_f32 v[104:105], v[122:123], v[104:105], s[42:43] op_sel_hi:[1,1,0]
	v_exp_f32_e32 v108, v108
	v_exp_f32_e32 v109, v109
	v_pk_fma_f32 v[104:105], v[122:123], v[104:105], s[44:45] op_sel_hi:[1,1,0]
	v_pk_mul_f32 v[104:105], v[122:123], v[104:105]
	v_and_b32_e32 v99, 0xffff0000, v99
	v_pk_mul_f32 v[104:105], v[108:109], v[104:105]
	v_pk_mul_f32 v[96:97], v[96:97], v[114:115]
	v_pk_mul_f32 v[108:109], v[106:107], v[104:105]
	v_pk_fma_f32 v[104:105], v[106:107], v[104:105], v[106:107] neg_lo:[1,0,0] neg_hi:[1,0,0]
	v_cvt_pk_bf16_f32 v96, v96, v97
	v_max_f32_e32 v105, v105, v109
	s_mov_b64 s[2:3], -1
	s_nop 0
	v_max_f32_e32 v104, v104, v108
	v_pk_mul_f32 v[98:99], v[104:105], v[98:99]
	s_and_b64 vcc, exec, s[48:49]
	v_cvt_pk_bf16_f32 v97, v98, v99
	s_cbranch_vccz .LBB0_2047
	s_mov_b64 s[2:3], 0

; __device__ __forceinline__ unsigned pk2(float lo, float hi) { const f32x2 v = {lo, hi}; const bf16x2_t b = __builtin_convertvector(v, bf16x2_t); return __builtin_bit_cast(unsigned, b); }
; __device__ __forceinline__ f32x2 gelu_pk(f32x2 v) {
;     const f32x2 av = __builtin_elementwise_abs(v), d = av * 0.2316418882f + 1.0f;
;     f32x2 t; t.x = __builtin_amdgcn_rcpf(d.x); t.y = __builtin_amdgcn_rcpf(d.y);
;     f32x2 q = t * 0.5307027145f + (-0.7265760135f); q = q * t + 0.7107068705f; q = q * t + (-0.142248368f); q = q * t + 0.127414796f; q = q * t;
;     const f32x2 s = (v * v) * (-0.72134752044f);
;     f32x2 e; e.x = __builtin_amdgcn_exp2f(s.x); e.y = __builtin_amdgcn_exp2f(s.y);
;     const f32x2 m = v * (q * e), r = v - m;
;     f32x2 o; o.x = v.x < 0.f ? m.x : r.x; o.y = v.y < 0.f ? m.y : r.y; return o;
; __device__ __forceinline__ void conv2d_phase(const Frame& F, int l, bool with_ctx, bool dry) {
;     ...
;         for (int t = 0; t < 8; ++t) {
;             f32x4 a = bias4;
; #pragma unroll
;             for (int dy = 0; dy < 3; ++dy)
; #pragma unroll
;                 for (int dx = 0; dx < 3; ++dx) {
;                     const u32x2 x = u[dy][t + dx]; const f32x4 ww = w[dy * 3 + dx];
;                     a.x += ww.x * bflo(x.x); a.y += ww.y * bfhi(x.x); a.z += ww.z * bflo(x.y); a.w += ww.w * bfhi(x.y);
;                 }
;             const f32x2 g0 = gelu_pk((f32x2){a.x, a.y}), g1 = gelu_pk((f32x2){a.z, a.w});
;             u32x2 o; o.x = pk2(g0.x * bflo(vv[t].x), g0.y * bfhi(vv[t].x)); o.y = pk2(g1.x * bflo(vv[t].y), g1.y * bfhi(vv[t].y));
;             bf16_t* vp = UV + (size_t)(tok0 + t) * NUP + FFN + ch;
;             if (!dry) *(u32x2*)vp = o; else asm volatile("" :: "v"(o));
.LBB0_2049:
	v_cndmask_b32_e64 v67, 0, v67, s[6:7]
	v_pk_fma_f32 v[108:109], v[36:37], v[118:119], v[40:41]
	v_lshlrev_b32_e32 v104, 16, v67
	v_and_b32_e32 v105, 0xffff0000, v67
	v_pk_fma_f32 v[108:109], v[20:21], v[112:113], v[108:109]
	v_cndmask_b32_e64 v71, 0, v71, s[76:77]
	v_pk_fma_f32 v[108:109], v[24:25], v[104:105], v[108:109]
	v_cndmask_b32_e64 v96, 0, v84, s[0:1]
	v_pk_fma_f32 v[94:95], v[28:29], v[94:95], v[108:109]
	v_cndmask_b32_e64 v97, 0, v85, s[0:1]
	v_lshlrev_b32_e32 v84, 16, v71
	v_and_b32_e32 v85, 0xffff0000, v71
	v_pk_fma_f32 v[94:95], v[32:33], v[90:91], v[94:95]
	v_cndmask_b32_e64 v66, 0, v66, s[6:7]
	v_pk_fma_f32 v[106:107], v[34:35], v[116:117], v[38:39]
	v_pk_fma_f32 v[94:95], v[12:13], v[84:85], v[94:95]
	v_lshlrev_b32_e32 v98, 16, v66
	v_and_b32_e32 v99, 0xffff0000, v66
	v_pk_fma_f32 v[94:95], v[16:17], v[100:101], v[94:95]
	v_pk_fma_f32 v[100:101], v[18:19], v[110:111], v[106:107]
	v_cndmask_b32_e64 v70, 0, v70, s[76:77]
	v_pk_fma_f32 v[100:101], v[22:23], v[98:99], v[100:101]
	v_lshlrev_b32_e32 v66, 16, v70
	v_pk_fma_f32 v[68:69], v[26:27], v[68:69], v[100:101]
	v_and_b32_e32 v67, 0xffff0000, v70
	v_pk_fma_f32 v[68:69], v[30:31], v[80:81], v[68:69]
	v_lshlrev_b32_e32 v70, 16, v96
	v_pk_fma_f32 v[68:69], v[10:11], v[66:67], v[68:69]
	v_and_b32_e32 v71, 0xffff0000, v96
	v_pk_fma_f32 v[68:69], v[14:15], v[92:93], v[68:69]
	v_mov_b64_e32 v[100:101], s[38:39]
	v_pk_fma_f32 v[68:69], v[2:3], v[82:83], v[68:69]
	v_lshlrev_b32_e32 v96, 16, v97
	v_pk_fma_f32 v[68:69], v[6:7], v[70:71], v[68:69]
	v_and_b32_e32 v97, 0xffff0000, v97
	v_and_b32_e32 v93, 0x7fffffff, v69
	v_and_b32_e32 v92, 0x7fffffff, v68
	v_pk_fma_f32 v[92:93], v[92:93], s[28:29], 1.0 op_sel_hi:[1,0,0]
	v_pk_mul_f32 v[108:109], v[68:69], v[68:69]
	v_rcp_f32_e32 v92, v92
	v_rcp_f32_e32 v93, v93
	v_pk_fma_f32 v[94:95], v[4:5], v[102:103], v[94:95]
	v_pk_mul_f32 v[108:109], v[108:109], s[46:47] op_sel_hi:[1,0]
	v_pk_fma_f32 v[94:95], v[8:9], v[96:97], v[94:95]
	v_pk_fma_f32 v[106:107], v[92:93], s[36:37], v[100:101] op_sel_hi:[1,0,0]
	v_exp_f32_e32 v108, v108
	v_pk_fma_f32 v[106:107], v[92:93], v[106:107], s[40:41] op_sel_hi:[1,1,0]
	v_exp_f32_e32 v109, v109
	v_pk_fma_f32 v[106:107], v[92:93], v[106:107], s[42:43] op_sel_hi:[1,1,0]
	v_and_b32_e32 v115, 0x7fffffff, v95
	v_and_b32_e32 v114, 0x7fffffff, v94
	v_pk_fma_f32 v[106:107], v[92:93], v[106:107], s[44:45] op_sel_hi:[1,1,0]
	v_pk_fma_f32 v[114:115], v[114:115], s[28:29], 1.0 op_sel_hi:[1,0,0]
	v_pk_mul_f32 v[92:93], v[92:93], v[106:107]
	v_rcp_f32_e32 v114, v114
	v_rcp_f32_e32 v115, v115
	v_pk_mul_f32 v[92:93], v[108:109], v[92:93]
	v_pk_mul_f32 v[108:109], v[68:69], v[92:93]
	v_pk_fma_f32 v[92:93], v[68:69], v[92:93], v[68:69] neg_lo:[1,0,0] neg_hi:[1,0,0]
	s_waitcnt vmcnt(4)
	v_lshlrev_b32_e32 v106, 16, v86
	v_max_f32_e32 v69, v93, v109
	v_and_b32_e32 v107, 0xffff0000, v86
	v_lshlrev_b32_e32 v86, 16, v87
	v_max_f32_e32 v68, v92, v108
	v_pk_fma_f32 v[92:93], v[114:115], s[36:37], v[100:101] op_sel_hi:[1,0,0]
	v_pk_mul_f32 v[100:101], v[94:95], v[94:95]
	v_pk_fma_f32 v[92:93], v[114:115], v[92:93], s[40:41] op_sel_hi:[1,1,0]
	v_pk_mul_f32 v[100:101], v[100:101], s[46:47] op_sel_hi:[1,0]
	v_pk_fma_f32 v[92:93], v[114:115], v[92:93], s[42:43] op_sel_hi:[1,1,0]
	v_exp_f32_e32 v100, v100
	v_exp_f32_e32 v101, v101
	v_pk_fma_f32 v[92:93], v[114:115], v[92:93], s[44:45] op_sel_hi:[1,1,0]
	v_pk_mul_f32 v[92:93], v[114:115], v[92:93]
	v_and_b32_e32 v87, 0xffff0000, v87
	v_pk_mul_f32 v[92:93], v[100:101], v[92:93]
	v_pk_mul_f32 v[68:69], v[68:69], v[106:107]
	v_pk_mul_f32 v[100:101], v[94:95], v[92:93]
	v_pk_fma_f32 v[92:93], v[94:95], v[92:93], v[94:95] neg_lo:[1,0,0] neg_hi:[1,0,0]
	v_cvt_pk_bf16_f32 v68, v68, v69
	v_max_f32_e32 v93, v93, v101
	s_mov_b64 s[0:1], -1
	s_nop 0
	v_max_f32_e32 v92, v92, v100
	v_pk_mul_f32 v[86:87], v[92:93], v[86:87]
	s_and_b64 vcc, exec, s[48:49]
	v_cvt_pk_bf16_f32 v69, v86, v87
	s_cbranch_vccz .LBB0_2051
	s_mov_b64 s[0:1], 0

; __device__ __forceinline__ unsigned pk2(float lo, float hi) { const f32x2 v = {lo, hi}; const bf16x2_t b = __builtin_convertvector(v, bf16x2_t); return __builtin_bit_cast(unsigned, b); }
; __device__ __forceinline__ f32x2 gelu_pk(f32x2 v) {
;     const f32x2 av = __builtin_elementwise_abs(v), d = av * 0.2316418882f + 1.0f;
;     f32x2 t; t.x = __builtin_amdgcn_rcpf(d.x); t.y = __builtin_amdgcn_rcpf(d.y);
;     f32x2 q = t * 0.5307027145f + (-0.7265760135f); q = q * t + 0.7107068705f; q = q * t + (-0.142248368f); q = q * t + 0.127414796f; q = q * t;
;     const f32x2 s = (v * v) * (-0.72134752044f);
;     f32x2 e; e.x = __builtin_amdgcn_exp2f(s.x); e.y = __builtin_amdgcn_exp2f(s.y);
;     const f32x2 m = v * (q * e), r = v - m;
;     f32x2 o; o.x = v.x < 0.f ? m.x : r.x; o.y = v.y < 0.f ? m.y : r.y; return o;
; __device__ __forceinline__ void conv2d_phase(const Frame& F, int l, bool with_ctx, bool dry) {
;     ...
;         for (int t = 0; t < 8; ++t) {
;             f32x4 a = bias4;
; #pragma unroll
;             for (int dy = 0; dy < 3; ++dy)
; #pragma unroll
;                 for (int dx = 0; dx < 3; ++dx) {
;                     const u32x2 x = u[dy][t + dx]; const f32x4 ww = w[dy * 3 + dx];
;                     a.x += ww.x * bflo(x.x); a.y += ww.y * bfhi(x.x); a.z += ww.z * bflo(x.y); a.w += ww.w * bfhi(x.y);
;                 }
;             const f32x2 g0 = gelu_pk((f32x2){a.x, a.y}), g1 = gelu_pk((f32x2){a.z, a.w});
;             u32x2 o; o.x = pk2(g0.x * bflo(vv[t].x), g0.y * bfhi(vv[t].x)); o.y = pk2(g1.x * bflo(vv[t].y), g1.y * bfhi(vv[t].y));
;             bf16_t* vp = UV + (size_t)(tok0 + t) * NUP + FFN + ch;
;             if (!dry) *(u32x2*)vp = o; else asm volatile("" :: "v"(o));
.LBB0_2053:
	v_readlane_b32 s50, v255, 27
	v_readlane_b32 s51, v255, 28
	v_pk_fma_f32 v[94:95], v[34:35], v[110:111], v[38:39]
	v_cndmask_b32_e64 v64, 0, v64, s[88:89]
	v_cndmask_b32_e64 v60, 0, v60, s[50:51]
	v_lshlrev_b32_e32 v86, 16, v60
	v_and_b32_e32 v87, 0xffff0000, v60
	v_pk_fma_f32 v[94:95], v[18:19], v[98:99], v[94:95]
	v_cndmask_b32_e64 v61, 0, v61, s[50:51]
	v_pk_fma_f32 v[94:95], v[22:23], v[86:87], v[94:95]
	v_lshlrev_b32_e32 v92, 16, v61
	v_pk_fma_f32 v[80:81], v[26:27], v[80:81], v[94:95]
	v_and_b32_e32 v93, 0xffff0000, v61
	v_lshlrev_b32_e32 v60, 16, v64
	v_and_b32_e32 v61, 0xffff0000, v64
	v_pk_fma_f32 v[80:81], v[30:31], v[66:67], v[80:81]
	v_cndmask_b32_e64 v65, 0, v65, s[88:89]
	v_pk_fma_f32 v[80:81], v[10:11], v[60:61], v[80:81]
	v_cndmask_b32_e64 v72, 0, v72, s[62:63]
	v_pk_fma_f32 v[80:81], v[14:15], v[82:83], v[80:81]
	v_lshlrev_b32_e32 v68, 16, v65
	v_and_b32_e32 v69, 0xffff0000, v65
	v_lshlrev_b32_e32 v64, 16, v72
	v_and_b32_e32 v65, 0xffff0000, v72
	v_pk_fma_f32 v[80:81], v[2:3], v[70:71], v[80:81]
	v_pk_fma_f32 v[100:101], v[36:37], v[112:113], v[40:41]
	v_pk_fma_f32 v[80:81], v[6:7], v[64:65], v[80:81]
	v_pk_fma_f32 v[100:101], v[20:21], v[104:105], v[100:101]
	v_and_b32_e32 v83, 0x7fffffff, v81
	v_and_b32_e32 v82, 0x7fffffff, v80
	v_pk_fma_f32 v[100:101], v[24:25], v[92:93], v[100:101]
	v_pk_fma_f32 v[82:83], v[82:83], s[28:29], 1.0 op_sel_hi:[1,0,0]
	v_pk_fma_f32 v[90:91], v[28:29], v[90:91], v[100:101]
	v_rcp_f32_e32 v82, v82
	v_rcp_f32_e32 v83, v83
	v_pk_fma_f32 v[90:91], v[32:33], v[84:85], v[90:91]
	v_cndmask_b32_e64 v73, 0, v73, s[62:63]
	v_pk_fma_f32 v[90:91], v[12:13], v[68:69], v[90:91]
	v_mov_b64_e32 v[94:95], s[38:39]
	v_pk_fma_f32 v[90:91], v[16:17], v[102:103], v[90:91]
	v_pk_mul_f32 v[102:103], v[80:81], v[80:81]
	v_lshlrev_b32_e32 v72, 16, v73
	v_and_b32_e32 v73, 0xffff0000, v73
	v_pk_fma_f32 v[90:91], v[4:5], v[96:97], v[90:91]
	v_pk_fma_f32 v[100:101], v[82:83], s[36:37], v[94:95] op_sel_hi:[1,0,0]
	v_pk_mul_f32 v[102:103], v[102:103], s[46:47] op_sel_hi:[1,0]
	v_pk_fma_f32 v[90:91], v[8:9], v[72:73], v[90:91]
	v_pk_fma_f32 v[100:101], v[82:83], v[100:101], s[40:41] op_sel_hi:[1,1,0]
	v_exp_f32_e32 v102, v102
	v_exp_f32_e32 v103, v103
	v_pk_fma_f32 v[100:101], v[82:83], v[100:101], s[42:43] op_sel_hi:[1,1,0]
	v_and_b32_e32 v107, 0x7fffffff, v91
	v_and_b32_e32 v106, 0x7fffffff, v90
	v_pk_fma_f32 v[100:101], v[82:83], v[100:101], s[44:45] op_sel_hi:[1,1,0]
	v_pk_fma_f32 v[106:107], v[106:107], s[28:29], 1.0 op_sel_hi:[1,0,0]
	v_pk_mul_f32 v[82:83], v[82:83], v[100:101]
	v_rcp_f32_e32 v106, v106
	v_rcp_f32_e32 v107, v107
	v_pk_mul_f32 v[82:83], v[102:103], v[82:83]
	v_pk_mul_f32 v[102:103], v[80:81], v[82:83]
	v_pk_fma_f32 v[82:83], v[80:81], v[82:83], v[80:81] neg_lo:[1,0,0] neg_hi:[1,0,0]
	s_waitcnt vmcnt(3)
	v_lshlrev_b32_e32 v100, 16, v76
	v_max_f32_e32 v81, v83, v103
	v_and_b32_e32 v101, 0xffff0000, v76
	s_mov_b64 s[0:1], -1
	v_max_f32_e32 v80, v82, v102
	v_pk_fma_f32 v[82:83], v[106:107], s[36:37], v[94:95] op_sel_hi:[1,0,0]
	v_pk_mul_f32 v[94:95], v[90:91], v[90:91]
	v_pk_fma_f32 v[82:83], v[106:107], v[82:83], s[40:41] op_sel_hi:[1,1,0]
	v_pk_mul_f32 v[94:95], v[94:95], s[46:47] op_sel_hi:[1,0]
	v_pk_fma_f32 v[82:83], v[106:107], v[82:83], s[42:43] op_sel_hi:[1,1,0]
	v_exp_f32_e32 v94, v94
	v_exp_f32_e32 v95, v95
	v_pk_fma_f32 v[82:83], v[106:107], v[82:83], s[44:45] op_sel_hi:[1,1,0]
	v_pk_mul_f32 v[82:83], v[106:107], v[82:83]
	v_pk_mul_f32 v[80:81], v[80:81], v[100:101]
	v_pk_mul_f32 v[82:83], v[94:95], v[82:83]
	v_cvt_pk_bf16_f32 v76, v80, v81
	v_pk_mul_f32 v[94:95], v[90:91], v[82:83]
	v_pk_fma_f32 v[82:83], v[90:91], v[82:83], v[90:91] neg_lo:[1,0,0] neg_hi:[1,0,0]
	v_lshlrev_b32_e32 v80, 16, v77
	v_max_f32_e32 v83, v83, v95
	v_and_b32_e32 v81, 0xffff0000, v77
	s_nop 0
	v_max_f32_e32 v82, v82, v94
	v_pk_mul_f32 v[80:81], v[82:83], v[80:81]
	s_and_b64 vcc, exec, s[48:49]
	v_cvt_pk_bf16_f32 v77, v80, v81
	s_cbranch_vccz .LBB0_2055
	s_mov_b64 s[0:1], 0

; __device__ __forceinline__ unsigned pk2(float lo, float hi) { const f32x2 v = {lo, hi}; const bf16x2_t b = __builtin_convertvector(v, bf16x2_t); return __builtin_bit_cast(unsigned, b); }
; __device__ __forceinline__ f32x2 gelu_pk(f32x2 v) {
;     const f32x2 av = __builtin_elementwise_abs(v), d = av * 0.2316418882f + 1.0f;
;     f32x2 t; t.x = __builtin_amdgcn_rcpf(d.x); t.y = __builtin_amdgcn_rcpf(d.y);
;     f32x2 q = t * 0.5307027145f + (-0.7265760135f); q = q * t + 0.7107068705f; q = q * t + (-0.142248368f); q = q * t + 0.127414796f; q = q * t;
;     const f32x2 s = (v * v) * (-0.72134752044f);
;     f32x2 e; e.x = __builtin_amdgcn_exp2f(s.x); e.y = __builtin_amdgcn_exp2f(s.y);
;     const f32x2 m = v * (q * e), r = v - m;
;     f32x2 o; o.x = v.x < 0.f ? m.x : r.x; o.y = v.y < 0.f ? m.y : r.y; return o;
; __device__ __forceinline__ void conv2d_phase(const Frame& F, int l, bool with_ctx, bool dry) {
;     ...
;         for (int t = 0; t < 8; ++t) {
;             f32x4 a = bias4;
; #pragma unroll
;             for (int dy = 0; dy < 3; ++dy)
; #pragma unroll
;                 for (int dx = 0; dx < 3; ++dx) {
;                     const u32x2 x = u[dy][t + dx]; const f32x4 ww = w[dy * 3 + dx];
;                     a.x += ww.x * bflo(x.x); a.y += ww.y * bfhi(x.x); a.z += ww.z * bflo(x.y); a.w += ww.w * bfhi(x.y);
;                 }
;             const f32x2 g0 = gelu_pk((f32x2){a.x, a.y}), g1 = gelu_pk((f32x2){a.z, a.w});
;             u32x2 o; o.x = pk2(g0.x * bflo(vv[t].x), g0.y * bfhi(vv[t].x)); o.y = pk2(g1.x * bflo(vv[t].y), g1.y * bfhi(vv[t].y));
;             bf16_t* vp = UV + (size_t)(tok0 + t) * NUP + FFN + ch;
;             if (!dry) *(u32x2*)vp = o; else asm volatile("" :: "v"(o));
.LBB0_2057:
	v_readlane_b32 s50, v255, 25
	v_readlane_b32 s51, v255, 26
	v_pk_fma_f32 v[90:91], v[34:35], v[98:99], v[38:39]
	v_cndmask_b32_e64 v76, 0, v58, s[74:75]
	v_cndmask_b32_e64 v54, 0, v54, s[50:51]
	v_lshlrev_b32_e32 v80, 16, v54
	v_and_b32_e32 v81, 0xffff0000, v54
	v_pk_fma_f32 v[90:91], v[18:19], v[86:87], v[90:91]
	v_cndmask_b32_e64 v77, 0, v59, s[74:75]
	v_pk_fma_f32 v[90:91], v[22:23], v[80:81], v[90:91]
	v_lshlrev_b32_e32 v58, 16, v76
	v_pk_fma_f32 v[66:67], v[26:27], v[66:67], v[90:91]
	v_and_b32_e32 v59, 0xffff0000, v76
	v_pk_fma_f32 v[66:67], v[30:31], v[60:61], v[66:67]
	v_cndmask_b32_e64 v55, 0, v55, s[50:51]
	v_pk_fma_f32 v[66:67], v[10:11], v[58:59], v[66:67]
	v_cndmask_b32_e64 v100, 0, v62, s[68:69]
	v_pk_fma_f32 v[66:67], v[14:15], v[70:71], v[66:67]
	v_lshlrev_b32_e32 v82, 16, v55
	v_and_b32_e32 v83, 0xffff0000, v55
	v_lshlrev_b32_e32 v54, 16, v100
	v_and_b32_e32 v55, 0xffff0000, v100
	v_pk_fma_f32 v[66:67], v[2:3], v[64:65], v[66:67]
	v_pk_fma_f32 v[94:95], v[36:37], v[104:105], v[40:41]
	v_pk_fma_f32 v[66:67], v[6:7], v[54:55], v[66:67]
	v_pk_fma_f32 v[94:95], v[20:21], v[92:93], v[94:95]
	v_and_b32_e32 v71, 0x7fffffff, v67
	v_and_b32_e32 v70, 0x7fffffff, v66
	v_pk_fma_f32 v[94:95], v[24:25], v[82:83], v[94:95]
	v_pk_fma_f32 v[70:71], v[70:71], s[28:29], 1.0 op_sel_hi:[1,0,0]
	v_pk_fma_f32 v[84:85], v[28:29], v[84:85], v[94:95]
	v_rcp_f32_e32 v70, v70
	v_rcp_f32_e32 v71, v71
	v_cndmask_b32_e64 v101, 0, v63, s[68:69]
	v_lshlrev_b32_e32 v62, 16, v77
	v_and_b32_e32 v63, 0xffff0000, v77
	v_pk_fma_f32 v[84:85], v[32:33], v[68:69], v[84:85]
	v_mov_b64_e32 v[90:91], s[38:39]
	v_pk_fma_f32 v[84:85], v[12:13], v[62:63], v[84:85]
	v_lshlrev_b32_e32 v76, 16, v101
	v_pk_fma_f32 v[84:85], v[16:17], v[96:97], v[84:85]
	v_pk_mul_f32 v[96:97], v[66:67], v[66:67]
	v_and_b32_e32 v77, 0xffff0000, v101
	v_pk_fma_f32 v[84:85], v[4:5], v[72:73], v[84:85]
	v_pk_fma_f32 v[94:95], v[70:71], s[36:37], v[90:91] op_sel_hi:[1,0,0]
	v_pk_mul_f32 v[96:97], v[96:97], s[46:47] op_sel_hi:[1,0]
	v_pk_fma_f32 v[84:85], v[8:9], v[76:77], v[84:85]
	v_pk_fma_f32 v[94:95], v[70:71], v[94:95], s[40:41] op_sel_hi:[1,1,0]
	v_exp_f32_e32 v96, v96
	v_exp_f32_e32 v97, v97
	v_pk_fma_f32 v[94:95], v[70:71], v[94:95], s[42:43] op_sel_hi:[1,1,0]
	v_and_b32_e32 v99, 0x7fffffff, v85
	v_and_b32_e32 v98, 0x7fffffff, v84
	v_pk_fma_f32 v[94:95], v[70:71], v[94:95], s[44:45] op_sel_hi:[1,1,0]
	v_pk_fma_f32 v[98:99], v[98:99], s[28:29], 1.0 op_sel_hi:[1,0,0]
	v_pk_mul_f32 v[70:71], v[70:71], v[94:95]
	v_rcp_f32_e32 v98, v98
	v_rcp_f32_e32 v99, v99
	v_pk_mul_f32 v[70:71], v[96:97], v[70:71]
	v_pk_mul_f32 v[96:97], v[66:67], v[70:71]
	v_pk_fma_f32 v[70:71], v[66:67], v[70:71], v[66:67] neg_lo:[1,0,0] neg_hi:[1,0,0]
	s_waitcnt vmcnt(2)
	v_lshlrev_b32_e32 v94, 16, v88
	v_max_f32_e32 v67, v71, v97
	v_and_b32_e32 v95, 0xffff0000, v88
	s_mov_b64 s[0:1], -1
	v_max_f32_e32 v66, v70, v96
	v_pk_fma_f32 v[70:71], v[98:99], s[36:37], v[90:91] op_sel_hi:[1,0,0]
	v_pk_mul_f32 v[90:91], v[84:85], v[84:85]
	v_pk_fma_f32 v[70:71], v[98:99], v[70:71], s[40:41] op_sel_hi:[1,1,0]
	v_pk_mul_f32 v[90:91], v[90:91], s[46:47] op_sel_hi:[1,0]
	v_pk_fma_f32 v[70:71], v[98:99], v[70:71], s[42:43] op_sel_hi:[1,1,0]
	v_exp_f32_e32 v90, v90
	v_exp_f32_e32 v91, v91
	v_pk_fma_f32 v[70:71], v[98:99], v[70:71], s[44:45] op_sel_hi:[1,1,0]
	v_pk_mul_f32 v[70:71], v[98:99], v[70:71]
	v_pk_mul_f32 v[66:67], v[66:67], v[94:95]
	v_pk_mul_f32 v[70:71], v[90:91], v[70:71]
	v_cvt_pk_bf16_f32 v66, v66, v67
	v_pk_mul_f32 v[90:91], v[84:85], v[70:71]
	v_pk_fma_f32 v[70:71], v[84:85], v[70:71], v[84:85] neg_lo:[1,0,0] neg_hi:[1,0,0]
	v_and_b32_e32 v85, 0xffff0000, v89
	v_max_f32_e32 v71, v71, v91
	v_lshlrev_b32_e32 v84, 16, v89
	s_nop 0
	v_max_f32_e32 v70, v70, v90
	v_pk_mul_f32 v[70:71], v[70:71], v[84:85]
	s_and_b64 vcc, exec, s[48:49]
	v_cvt_pk_bf16_f32 v67, v70, v71
	s_cbranch_vccz .LBB0_2059
	s_mov_b64 s[0:1], 0

; __device__ __forceinline__ unsigned pk2(float lo, float hi) { const f32x2 v = {lo, hi}; const bf16x2_t b = __builtin_convertvector(v, bf16x2_t); return __builtin_bit_cast(unsigned, b); }
; __device__ __forceinline__ f32x2 gelu_pk(f32x2 v) {
;     const f32x2 av = __builtin_elementwise_abs(v), d = av * 0.2316418882f + 1.0f;
;     f32x2 t; t.x = __builtin_amdgcn_rcpf(d.x); t.y = __builtin_amdgcn_rcpf(d.y);
;     f32x2 q = t * 0.5307027145f + (-0.7265760135f); q = q * t + 0.7107068705f; q = q * t + (-0.142248368f); q = q * t + 0.127414796f; q = q * t;
;     const f32x2 s = (v * v) * (-0.72134752044f);
;     f32x2 e; e.x = __builtin_amdgcn_exp2f(s.x); e.y = __builtin_amdgcn_exp2f(s.y);
;     const f32x2 m = v * (q * e), r = v - m;
;     f32x2 o; o.x = v.x < 0.f ? m.x : r.x; o.y = v.y < 0.f ? m.y : r.y; return o;
; __device__ __forceinline__ void conv2d_phase(const Frame& F, int l, bool with_ctx, bool dry) {
;     ...
;         for (int t = 0; t < 8; ++t) {
;             f32x4 a = bias4;
; #pragma unroll
;             for (int dy = 0; dy < 3; ++dy)
; #pragma unroll
;                 for (int dx = 0; dx < 3; ++dx) {
;                     const u32x2 x = u[dy][t + dx]; const f32x4 ww = w[dy * 3 + dx];
;                     a.x += ww.x * bflo(x.x); a.y += ww.y * bfhi(x.x); a.z += ww.z * bflo(x.y); a.w += ww.w * bfhi(x.y);
;                 }
;             const f32x2 g0 = gelu_pk((f32x2){a.x, a.y}), g1 = gelu_pk((f32x2){a.z, a.w});
;             u32x2 o; o.x = pk2(g0.x * bflo(vv[t].x), g0.y * bfhi(vv[t].x)); o.y = pk2(g1.x * bflo(vv[t].y), g1.y * bfhi(vv[t].y));
;             bf16_t* vp = UV + (size_t)(tok0 + t) * NUP + FFN + ch;
;             if (!dry) *(u32x2*)vp = o; else asm volatile("" :: "v"(o));
.LBB0_2061:
	v_readlane_b32 s50, v255, 23
	v_readlane_b32 s51, v255, 24
	v_pk_fma_f32 v[88:89], v[36:37], v[92:93], v[40:41]
	v_cndmask_b32_e64 v85, 0, v53, s[70:71]
	v_cndmask_b32_e64 v49, 0, v49, s[50:51]
	v_lshlrev_b32_e32 v70, 16, v49
	v_and_b32_e32 v71, 0xffff0000, v49
	v_pk_fma_f32 v[88:89], v[20:21], v[82:83], v[88:89]
	v_lshlrev_b32_e32 v84, 16, v85
	v_pk_fma_f32 v[88:89], v[24:25], v[70:71], v[88:89]
	v_and_b32_e32 v85, 0xffff0000, v85
	v_pk_fma_f32 v[68:69], v[28:29], v[68:69], v[88:89]
	v_cndmask_b32_e64 v48, 0, v48, s[50:51]
	v_pk_fma_f32 v[68:69], v[32:33], v[62:63], v[68:69]
	v_pk_fma_f32 v[86:87], v[34:35], v[86:87], v[38:39]
	v_pk_fma_f32 v[68:69], v[12:13], v[84:85], v[68:69]
	v_cndmask_b32_e64 v67, 0, v52, s[70:71]
	v_lshlrev_b32_e32 v52, 16, v48
	v_and_b32_e32 v53, 0xffff0000, v48
	v_pk_fma_f32 v[68:69], v[16:17], v[72:73], v[68:69]
	v_pk_fma_f32 v[72:73], v[18:19], v[80:81], v[86:87]
	v_lshlrev_b32_e32 v66, 16, v67
	v_pk_fma_f32 v[72:73], v[22:23], v[52:53], v[72:73]
	v_and_b32_e32 v67, 0xffff0000, v67
	v_pk_fma_f32 v[60:61], v[26:27], v[60:61], v[72:73]
	v_cndmask_b32_e64 v90, 0, v56, s[16:17]
	v_pk_fma_f32 v[60:61], v[30:31], v[58:59], v[60:61]
	v_cndmask_b32_e64 v91, 0, v57, s[16:17]
	v_pk_fma_f32 v[60:61], v[10:11], v[66:67], v[60:61]
	v_lshlrev_b32_e32 v56, 16, v90
	v_pk_fma_f32 v[60:61], v[14:15], v[64:65], v[60:61]
	v_and_b32_e32 v57, 0xffff0000, v90
	v_pk_fma_f32 v[60:61], v[2:3], v[54:55], v[60:61]
	v_mov_b64_e32 v[72:73], s[38:39]
	v_pk_fma_f32 v[60:61], v[6:7], v[56:57], v[60:61]
	v_lshlrev_b32_e32 v48, 16, v91
	v_and_b32_e32 v65, 0x7fffffff, v61
	v_and_b32_e32 v64, 0x7fffffff, v60
	v_pk_fma_f32 v[64:65], v[64:65], s[28:29], 1.0 op_sel_hi:[1,0,0]
	v_pk_mul_f32 v[88:89], v[60:61], v[60:61]
	v_rcp_f32_e32 v64, v64
	v_rcp_f32_e32 v65, v65
	v_and_b32_e32 v49, 0xffff0000, v91
	v_pk_fma_f32 v[68:69], v[4:5], v[76:77], v[68:69]
	v_pk_mul_f32 v[88:89], v[88:89], s[46:47] op_sel_hi:[1,0]
	v_pk_fma_f32 v[86:87], v[64:65], s[36:37], v[72:73] op_sel_hi:[1,0,0]
	v_pk_fma_f32 v[68:69], v[8:9], v[48:49], v[68:69]
	v_pk_fma_f32 v[86:87], v[64:65], v[86:87], s[40:41] op_sel_hi:[1,1,0]
	v_exp_f32_e32 v88, v88
	v_exp_f32_e32 v89, v89
	v_pk_fma_f32 v[86:87], v[64:65], v[86:87], s[42:43] op_sel_hi:[1,1,0]
	v_and_b32_e32 v91, 0x7fffffff, v69
	v_and_b32_e32 v90, 0x7fffffff, v68
	v_pk_fma_f32 v[86:87], v[64:65], v[86:87], s[44:45] op_sel_hi:[1,1,0]
	v_pk_fma_f32 v[90:91], v[90:91], s[28:29], 1.0 op_sel_hi:[1,0,0]
	v_pk_mul_f32 v[64:65], v[64:65], v[86:87]
	v_rcp_f32_e32 v90, v90
	v_rcp_f32_e32 v91, v91
	v_pk_mul_f32 v[64:65], v[88:89], v[64:65]
	v_pk_mul_f32 v[88:89], v[60:61], v[64:65]
	v_pk_fma_f32 v[64:65], v[60:61], v[64:65], v[60:61] neg_lo:[1,0,0] neg_hi:[1,0,0]
	s_waitcnt vmcnt(1)
	v_lshlrev_b32_e32 v86, 16, v78
	v_max_f32_e32 v61, v65, v89
	v_and_b32_e32 v87, 0xffff0000, v78
	s_mov_b64 s[0:1], -1
	v_max_f32_e32 v60, v64, v88
	v_pk_fma_f32 v[64:65], v[90:91], s[36:37], v[72:73] op_sel_hi:[1,0,0]
	v_pk_mul_f32 v[72:73], v[68:69], v[68:69]
	v_pk_fma_f32 v[64:65], v[90:91], v[64:65], s[40:41] op_sel_hi:[1,1,0]
	v_pk_mul_f32 v[72:73], v[72:73], s[46:47] op_sel_hi:[1,0]
	v_pk_fma_f32 v[64:65], v[90:91], v[64:65], s[42:43] op_sel_hi:[1,1,0]
	v_exp_f32_e32 v72, v72
	v_exp_f32_e32 v73, v73
	v_pk_fma_f32 v[64:65], v[90:91], v[64:65], s[44:45] op_sel_hi:[1,1,0]
	v_pk_mul_f32 v[64:65], v[90:91], v[64:65]
	v_pk_mul_f32 v[60:61], v[60:61], v[86:87]
	v_pk_mul_f32 v[64:65], v[72:73], v[64:65]
	v_cvt_pk_bf16_f32 v60, v60, v61
	v_pk_mul_f32 v[72:73], v[68:69], v[64:65]
	v_pk_fma_f32 v[64:65], v[68:69], v[64:65], v[68:69] neg_lo:[1,0,0] neg_hi:[1,0,0]
	v_and_b32_e32 v69, 0xffff0000, v79
	v_max_f32_e32 v65, v65, v73
	v_lshlrev_b32_e32 v68, 16, v79
	s_nop 0
	v_max_f32_e32 v64, v64, v72
	v_pk_mul_f32 v[64:65], v[64:65], v[68:69]
	s_and_b64 vcc, exec, s[48:49]
	v_cvt_pk_bf16_f32 v61, v64, v65
	s_cbranch_vccz .LBB0_2063
	s_mov_b64 s[0:1], 0

; __device__ __forceinline__ unsigned pk2(float lo, float hi) { const f32x2 v = {lo, hi}; const bf16x2_t b = __builtin_convertvector(v, bf16x2_t); return __builtin_bit_cast(unsigned, b); }
; __device__ __forceinline__ f32x2 gelu_pk(f32x2 v) {
;     const f32x2 av = __builtin_elementwise_abs(v), d = av * 0.2316418882f + 1.0f;
;     f32x2 t; t.x = __builtin_amdgcn_rcpf(d.x); t.y = __builtin_amdgcn_rcpf(d.y);
;     f32x2 q = t * 0.5307027145f + (-0.7265760135f); q = q * t + 0.7107068705f; q = q * t + (-0.142248368f); q = q * t + 0.127414796f; q = q * t;
;     const f32x2 s = (v * v) * (-0.72134752044f);
;     f32x2 e; e.x = __builtin_amdgcn_exp2f(s.x); e.y = __builtin_amdgcn_exp2f(s.y);
;     const f32x2 m = v * (q * e), r = v - m;
;     f32x2 o; o.x = v.x < 0.f ? m.x : r.x; o.y = v.y < 0.f ? m.y : r.y; return o;
; __device__ __forceinline__ void conv2d_phase(const Frame& F, int l, bool with_ctx, bool dry) {
;     ...
;         for (int t = 0; t < 8; ++t) {
;             f32x4 a = bias4;
; #pragma unroll
;             for (int dy = 0; dy < 3; ++dy)
; #pragma unroll
;                 for (int dx = 0; dx < 3; ++dx) {
;                     const u32x2 x = u[dy][t + dx]; const f32x4 ww = w[dy * 3 + dx];
;                     a.x += ww.x * bflo(x.x); a.y += ww.y * bfhi(x.x); a.z += ww.z * bflo(x.y); a.w += ww.w * bfhi(x.y);
;                 }
;             const f32x2 g0 = gelu_pk((f32x2){a.x, a.y}), g1 = gelu_pk((f32x2){a.z, a.w});
;             u32x2 o; o.x = pk2(g0.x * bflo(vv[t].x), g0.y * bfhi(vv[t].x)); o.y = pk2(g1.x * bflo(vv[t].y), g1.y * bfhi(vv[t].y));
;             bf16_t* vp = UV + (size_t)(tok0 + t) * NUP + FFN + ch;
;             if (!dry) *(u32x2*)vp = o; else asm volatile("" :: "v"(o));
.LBB0_2065:
	v_cndmask_b32_e64 v45, 0, v45, s[72:73]
	v_pk_fma_f32 v[36:37], v[36:37], v[82:83], v[40:41]
	v_lshlrev_b32_e32 v40, 16, v45
	v_and_b32_e32 v41, 0xffff0000, v45
	v_pk_fma_f32 v[20:21], v[20:21], v[70:71], v[36:37]
	v_cndmask_b32_e64 v44, 0, v44, s[72:73]
	v_pk_fma_f32 v[20:21], v[24:25], v[40:41], v[20:21]
	v_cndmask_b32_e64 v46, 0, v46, s[66:67]
	v_cndmask_b32_e64 v47, 0, v47, s[66:67]
	v_pk_fma_f32 v[20:21], v[28:29], v[62:63], v[20:21]
	v_pk_fma_f32 v[34:35], v[34:35], v[80:81], v[38:39]
	v_lshlrev_b32_e32 v38, 16, v44
	v_and_b32_e32 v39, 0xffff0000, v44
	v_lshlrev_b32_e32 v44, 16, v46
	v_and_b32_e32 v45, 0xffff0000, v46
	v_lshlrev_b32_e32 v46, 16, v47
	v_and_b32_e32 v47, 0xffff0000, v47
	v_pk_fma_f32 v[20:21], v[32:33], v[84:85], v[20:21]
	v_cndmask_b32_e64 v60, 0, v50, s[10:11]
	v_pk_fma_f32 v[12:13], v[12:13], v[46:47], v[20:21]
	v_cndmask_b32_e64 v61, 0, v51, s[10:11]
	v_pk_fma_f32 v[12:13], v[16:17], v[76:77], v[12:13]
	v_pk_fma_f32 v[16:17], v[18:19], v[52:53], v[34:35]
	v_lshlrev_b32_e32 v50, 16, v60
	v_pk_fma_f32 v[16:17], v[22:23], v[38:39], v[16:17]
	v_and_b32_e32 v51, 0xffff0000, v60
	v_pk_fma_f32 v[16:17], v[26:27], v[58:59], v[16:17]
	v_lshlrev_b32_e32 v60, 16, v61
	v_pk_fma_f32 v[16:17], v[30:31], v[66:67], v[16:17]
	v_and_b32_e32 v61, 0xffff0000, v61
	v_pk_fma_f32 v[10:11], v[10:11], v[44:45], v[16:17]
	v_pk_fma_f32 v[4:5], v[4:5], v[48:49], v[12:13]
	v_pk_fma_f32 v[10:11], v[14:15], v[54:55], v[10:11]
	v_pk_fma_f32 v[4:5], v[8:9], v[60:61], v[4:5]
	v_pk_fma_f32 v[2:3], v[2:3], v[56:57], v[10:11]
	v_mov_b64_e32 v[8:9], s[38:39]
	v_pk_fma_f32 v[2:3], v[6:7], v[50:51], v[2:3]
	v_and_b32_e32 v15, 0x7fffffff, v5
	v_and_b32_e32 v7, 0x7fffffff, v3
	v_and_b32_e32 v6, 0x7fffffff, v2
	v_pk_fma_f32 v[6:7], v[6:7], s[28:29], 1.0 op_sel_hi:[1,0,0]
	v_pk_mul_f32 v[12:13], v[2:3], v[2:3]
	v_rcp_f32_e32 v6, v6
	v_rcp_f32_e32 v7, v7
	v_pk_mul_f32 v[12:13], v[12:13], s[46:47] op_sel_hi:[1,0]
	v_and_b32_e32 v14, 0x7fffffff, v4
	v_exp_f32_e32 v12, v12
	v_pk_fma_f32 v[10:11], v[6:7], s[36:37], v[8:9] op_sel_hi:[1,0,0]
	v_exp_f32_e32 v13, v13
	v_pk_fma_f32 v[10:11], v[6:7], v[10:11], s[40:41] op_sel_hi:[1,1,0]
	v_pk_fma_f32 v[14:15], v[14:15], s[28:29], 1.0 op_sel_hi:[1,0,0]
	v_pk_fma_f32 v[10:11], v[6:7], v[10:11], s[42:43] op_sel_hi:[1,1,0]
	v_rcp_f32_e32 v14, v14
	v_pk_fma_f32 v[10:11], v[6:7], v[10:11], s[44:45] op_sel_hi:[1,1,0]
	v_rcp_f32_e32 v15, v15
	v_pk_mul_f32 v[6:7], v[6:7], v[10:11]
	v_pk_mul_f32 v[6:7], v[12:13], v[6:7]
	s_waitcnt vmcnt(0)
	v_lshlrev_b32_e32 v10, 16, v74
	v_pk_mul_f32 v[12:13], v[2:3], v[6:7]
	v_pk_fma_f32 v[6:7], v[2:3], v[6:7], v[2:3] neg_lo:[1,0,0] neg_hi:[1,0,0]
	v_and_b32_e32 v11, 0xffff0000, v74
	v_max_f32_e32 v3, v7, v13
	s_mov_b64 s[0:1], -1
	s_nop 0
	v_max_f32_e32 v2, v6, v12
	v_pk_fma_f32 v[6:7], v[14:15], s[36:37], v[8:9] op_sel_hi:[1,0,0]
	v_pk_mul_f32 v[8:9], v[4:5], v[4:5]
	v_pk_fma_f32 v[6:7], v[14:15], v[6:7], s[40:41] op_sel_hi:[1,1,0]
	v_pk_mul_f32 v[8:9], v[8:9], s[46:47] op_sel_hi:[1,0]
	v_pk_fma_f32 v[6:7], v[14:15], v[6:7], s[42:43] op_sel_hi:[1,1,0]
	v_exp_f32_e32 v8, v8
	v_exp_f32_e32 v9, v9
	v_pk_fma_f32 v[6:7], v[14:15], v[6:7], s[44:45] op_sel_hi:[1,1,0]
	v_pk_mul_f32 v[6:7], v[14:15], v[6:7]
	v_pk_mul_f32 v[2:3], v[2:3], v[10:11]
	v_pk_mul_f32 v[6:7], v[8:9], v[6:7]
	v_cvt_pk_bf16_f32 v2, v2, v3
	v_pk_mul_f32 v[8:9], v[4:5], v[6:7]
	v_pk_fma_f32 v[6:7], v[4:5], v[6:7], v[4:5] neg_lo:[1,0,0] neg_hi:[1,0,0]
	s_nop 0
	v_max_f32_e32 v5, v7, v9
	v_and_b32_e32 v7, 0xffff0000, v75
	s_nop 0
	v_max_f32_e32 v4, v6, v8
	v_lshlrev_b32_e32 v6, 16, v75
	v_pk_mul_f32 v[4:5], v[4:5], v[6:7]
	s_and_b64 vcc, exec, s[48:49]
	v_cvt_pk_bf16_f32 v3, v4, v5
	s_cbranch_vccz .LBB0_2067
	s_mov_b64 s[0:1], 0
